# baseline (speedup 1.0000x reference)
; __device__ __forceinline__ unsigned xb_add(unsigned* p, unsigned v) { return __hip_atomic_fetch_add(p, v, __ATOMIC_RELAXED, __HIP_MEMORY_SCOPE_AGENT); }
; __device__ __forceinline__ void xcd_barrier(unsigned* bar, volatile LAS unsigned* st) {
;     ...
;         const unsigned old = xb_add(&bar[XB_XSUB(x)], 1u);
;         const unsigned gen = old / nloc;
;         if (old + 1u == (gen + 1u) * nloc) {
;             __builtin_amdgcn_fence(__ATOMIC_RELEASE, "agent");
;             asm volatile("s_waitcnt vmcnt(0)" ::: "memory");
;             const unsigned og = xb_add(&bar[XB_TOP], 1u);
.LBB0_435:
	s_andn2_saveexec_b64 s[12:13], s[16:17]
	s_cbranch_execz .LBB0_455
	s_mov_b64 s[12:13], exec
	s_waitcnt lgkmcnt(0)
	s_and_b32 s99, s98, s92
	s_cbranch_scc1 .Lxl_skip_d
	s_cmp_lg_u32 s98, 0
	s_cbranch_scc1 .Lxl_nowb_d
	buffer_wbl2 sc1
	s_waitcnt vmcnt(0)
.Lxl_nowb_d:
	v_mbcnt_lo_u32_b32 v0, s12, 0
	v_mbcnt_hi_u32_b32 v0, s13, v0
	v_cmp_eq_u32_e32 vcc, 0, v0
	s_and_saveexec_b64 s[16:17], vcc
	s_cbranch_execz .LBB0_438
	s_bcnt1_i32_b64 s12, s[12:13]
	v_mov_b32_e32 v3, s12
	v_mov_b32_e32 v4, 0x12b93000
	global_atomic_add v3, v4, v3, s[8:9] offset:1024 sc0
